# NSA selected branch visits the union's blocks newest first so the running max settles early and the accumulator rescale path is rarely taken (online softmax is order independent)
# speedup vs baseline: 1.0032x; 1.0032x over previous
; #define NSA_LOADT(kb_, vb_, pitch_) do { int ln_ = lane; asm volatile("" : "+v"(ln_));   \
;         kreg = *(const u32x4*)((kb_) + (unsigned)(ln_ * (pitch_) + wid * 8)); vreg = *(const u32x4*)((vb_) + (unsigned)((16 * (wid & 3) + (ln_ >> 2)) * (pitch_) + (wid >> 2) * 32 + (ln_ & 3) * 8)); } while (0)
; #define NSA_STORET(slot_) do { *(LAS u32x4*)(lds + NL_KS + (slot_) * 8192 + wid * 1024 + lane * 16) = kreg; *(LAS u32x4*)(lds + NL_VS + (slot_) * 8192 + wid * 1024 + lane * 16) = vreg; } while (0)
; __device__ __forceinline__ void nsa_unit(const Ctx& c, int l, int b, int n, int qt) {
;     ...
;     const unsigned long long mq = maskb[tq];
;     unsigned long long uni;
;     { unsigned lo = (unsigned)maskb[lane], hi32 = (unsigned)(maskb[lane] >> 32);
; #pragma unroll
;       for (int o = 1; o < 64; o <<= 1) { lo |= (unsigned)__shfl_xor((int)lo, o); hi32 |= (unsigned)__shfl_xor((int)hi32, o); }
;       uni = ((unsigned long long)(unsigned)__builtin_amdgcn_readfirstlane((int)hi32) << 32) | (unsigned)__builtin_amdgcn_readfirstlane((int)lo); }
;     {
;         NsaSm st; nsa_sm_init(st);
;         const bf16* Kb = H + rowbase * HW + HKV + 256 + n * 64; const bf16* Vb = Kb + 128;
;         unsigned long long rem = uni; int j = __builtin_ctzll(rem); rem &= rem - 1;
;         NSA_LOADT(Kb + (size_t)j * 64 * HW, Vb + (size_t)j * 64 * HW, HW); NSA_STORET(0); __syncthreads();
;         int cur = 0;
;         for (;;) {
;             const bool more = rem != 0ull; int jn = 0;
;             if (more) { jn = __builtin_ctzll(rem); rem &= rem - 1; NSA_LOADT(Kb + (size_t)jn * 64 * HW, Vb + (size_t)jn * 64 * HW, HW); }
.LBB0_1322:
	s_add_i32 s2, 0, 0x18800
	v_lshl_add_u32 v0, v247, 3, s2
	v_lshl_add_u32 v5, v154, 3, s2
	s_waitcnt lgkmcnt(0)
	s_barrier
	ds_read_b64 v[2:3], v0
	ds_read_b64 v[152:153], v5
	v_and_b32_e32 v0, 64, v223
	v_add_u32_e32 v0, 64, v0
	v_xor_b32_e32 v4, 1, v223
	v_cmp_lt_i32_e32 vcc, v4, v0
	s_mul_i32 s16, s16, 0x1c00000
	s_add_u32 s4, s44, s16
	v_cndmask_b32_e32 v4, v223, v4, vcc
	v_lshlrev_b32_e32 v4, 2, v4
	s_waitcnt lgkmcnt(1)
	ds_bpermute_b32 v5, v4, v2
	ds_bpermute_b32 v4, v4, v3
	s_addc_u32 s5, s45, 0
	s_lshl_b32 s6, s17, 1
	s_add_u32 s28, s4, s6
	s_waitcnt lgkmcnt(1)
	v_or_b32_e32 v2, v5, v2
	s_waitcnt lgkmcnt(0)
	v_or_b32_e32 v3, v4, v3
	v_xor_b32_e32 v4, 2, v223
	v_cmp_lt_i32_e32 vcc, v4, v0
	s_addc_u32 s29, s5, 0
	v_mov_b32_e32 v14, v1
	v_cndmask_b32_e32 v4, v223, v4, vcc
	v_lshlrev_b32_e32 v4, 2, v4
	ds_bpermute_b32 v5, v4, v2
	ds_bpermute_b32 v4, v4, v3
	v_mov_b32_e32 v15, v1
	v_mov_b32_e32 v6, v1
	v_mov_b32_e32 v7, v1
	s_waitcnt lgkmcnt(1)
	v_or_b32_e32 v2, v5, v2
	s_waitcnt lgkmcnt(0)
	v_or_b32_e32 v3, v4, v3
	v_xor_b32_e32 v4, 4, v223
	v_cmp_lt_i32_e32 vcc, v4, v0
	v_mov_b32_e32 v8, v1
	v_mov_b32_e32 v9, v1
	v_cndmask_b32_e32 v4, v223, v4, vcc
	v_lshlrev_b32_e32 v4, 2, v4
	ds_bpermute_b32 v5, v4, v2
	ds_bpermute_b32 v4, v4, v3
	v_mov_b32_e32 v10, v1
	v_mov_b32_e32 v11, v1
	v_mov_b32_e32 v12, v1
	s_waitcnt lgkmcnt(1)
	v_or_b32_e32 v2, v5, v2
	s_waitcnt lgkmcnt(0)
	v_or_b32_e32 v3, v4, v3
	v_xor_b32_e32 v4, 8, v223
	v_cmp_lt_i32_e32 vcc, v4, v0
	v_mov_b32_e32 v13, v1
	v_mov_b32_e32 v252, v223
	v_cndmask_b32_e32 v4, v223, v4, vcc
	v_lshlrev_b32_e32 v4, 2, v4
	ds_bpermute_b32 v5, v4, v2
	ds_bpermute_b32 v4, v4, v3
	s_mov_b32 s42, 0
	v_mul_f32_e32 v249, v240, v112
	v_mov_b32_e32 v242, v240
	s_waitcnt lgkmcnt(1)
	v_or_b32_e32 v2, v5, v2
	s_waitcnt lgkmcnt(0)
	v_or_b32_e32 v3, v4, v3
	v_xor_b32_e32 v4, 16, v223
	v_cmp_lt_i32_e32 vcc, v4, v0
	v_mov_b32_e32 v243, v240
	v_mov_b32_e32 v244, v240
	v_cndmask_b32_e32 v4, v223, v4, vcc
	v_lshlrev_b32_e32 v4, 2, v4
	ds_bpermute_b32 v5, v4, v2
	ds_bpermute_b32 v4, v4, v3
	v_mov_b32_e32 v245, v240
	v_mov_b32_e32 v158, 0xc61c4000
	v_mov_b32_e32 v157, 0
	s_waitcnt lgkmcnt(1)
	v_or_b32_e32 v2, v5, v2
	s_waitcnt lgkmcnt(0)
	v_or_b32_e32 v3, v4, v3
	v_xor_b32_e32 v4, 32, v223
	v_cmp_lt_i32_e32 vcc, v4, v0
	s_nop 1
	v_cndmask_b32_e32 v0, v223, v4, vcc
	v_lshlrev_b32_e32 v0, 2, v0
	ds_bpermute_b32 v4, v0, v2
	ds_bpermute_b32 v0, v0, v3
	s_waitcnt lgkmcnt(1)
	v_or_b32_e32 v2, v4, v2
	s_waitcnt lgkmcnt(0)
	v_or_b32_e32 v0, v0, v3
	v_readfirstlane_b32 s2, v2
	v_readfirstlane_b32 s3, v0
	s_flbit_i32_b64 s8, s[2:3]
	s_sub_i32 s8, 63, s8
	s_bitset0_b64 s[2:3], s8
	v_mov_b32_e32 v4, v247
	s_mul_i32 s4, s8, 0x70000
	s_add_u32 s4, s28, s4
	v_mul_lo_u32 v0, v4, s21
	s_addc_u32 s5, s29, 0
	v_add_u32_e32 v0, s1, v0
	v_lshl_add_u64 v[2:3], v[0:1], 1, s[4:5]
	v_lshrrev_b32_e32 v0, 2, v4
	v_add_u32_e32 v0, s22, v0
	v_mul_lo_u32 v0, v0, s21
	v_add_u32_e32 v0, s23, v0
	v_lshlrev_b32_e32 v4, 3, v4
	v_and_or_b32 v0, v4, 24, v0
	v_lshl_add_u64 v[4:5], v[0:1], 1, s[4:5]
	global_load_dwordx4 v[144:147], v[2:3], off offset:1536
	global_load_dwordx4 v[148:151], v[4:5], off offset:1792
	v_mov_b32_e32 v2, v1
	v_mov_b32_e32 v3, v1
	v_mov_b32_e32 v4, v1
	v_mov_b32_e32 v5, v1
	v_mov_b32_e32 v0, v1
	v_mov_b64_e32 v[62:63], v[14:15]
	v_mov_b64_e32 v[78:79], v[14:15]
	v_mov_b64_e32 v[60:61], v[12:13]
	v_mov_b64_e32 v[58:59], v[10:11]
	v_mov_b64_e32 v[56:57], v[8:9]
	v_mov_b64_e32 v[54:55], v[6:7]
	v_mov_b64_e32 v[52:53], v[4:5]
	v_mov_b64_e32 v[50:51], v[2:3]
	v_mov_b64_e32 v[48:49], v[0:1]
	v_mov_b64_e32 v[76:77], v[12:13]
	v_mov_b64_e32 v[74:75], v[10:11]
	v_mov_b64_e32 v[72:73], v[8:9]
	v_mov_b64_e32 v[70:71], v[6:7]
	v_mov_b64_e32 v[68:69], v[4:5]
	v_mov_b64_e32 v[66:67], v[2:3]
	v_mov_b64_e32 v[64:65], v[0:1]
	s_waitcnt vmcnt(1)
	ds_write_b128 v251, v[144:147] offset:1024
	s_waitcnt vmcnt(0)
	ds_write_b128 v251, v[148:151] offset:17408
	s_waitcnt lgkmcnt(0)
	s_barrier
.LBB0_1323:
	s_cmp_eq_u64 s[2:3], 0
	s_cselect_b64 s[6:7], -1, 0
	s_cmp_lg_u64 s[2:3], 0
	s_mov_b64 s[4:5], 0
	s_cselect_b64 s[36:37], -1, 0
	s_and_b64 vcc, exec, s[6:7]
	s_mov_b32 s43, 0
	s_cbranch_vccnz .LBB0_1325
	s_flbit_i32_b64 s43, s[2:3]
	s_sub_i32 s43, 63, s43
	s_mov_b64 s[4:5], s[2:3]
	s_bitset0_b64 s[4:5], s43
	v_mov_b32_e32 v4, v247
	s_mul_i32 s2, s43, 0x70000
	s_add_u32 s2, s28, s2
	v_mul_lo_u32 v0, v4, s21
	s_addc_u32 s3, s29, 0
	v_add_u32_e32 v0, s1, v0
	v_lshl_add_u64 v[2:3], v[0:1], 1, s[2:3]
	v_lshrrev_b32_e32 v0, 2, v4
	v_add_u32_e32 v0, s22, v0
	v_mul_lo_u32 v0, v0, s21
	v_add_u32_e32 v0, s23, v0
	v_lshlrev_b32_e32 v4, 3, v4
	v_and_or_b32 v0, v4, 24, v0
	v_lshl_add_u64 v[4:5], v[0:1], 1, s[2:3]
	global_load_dwordx4 v[144:147], v[2:3], off offset:1536
	global_load_dwordx4 v[148:151], v[4:5], off offset:1792
